# w_in[l+1] conversion returned to the cscan side waves (only w_ff1/w_ff2 ride in the G1 epilogues): balances the scan-bound cscan phase against G1 epilogue overhead
# speedup vs baseline: 1.0123x; 1.0001x over previous
.Lcv_win:
	s_branch .Lcv_none
	s_cmp_eq_u32 s15, 3
	s_cbranch_scc1 .Lcv_none
	s_sub_u32 s13, s13, 0x4000
	s_mul_hi_u32 s32, s13, 0x1111112
	s_mul_i32 s41, s32, 0xf0
	s_sub_u32 s41, s13, s41
	v_mov_b32_e32 v192, 0x20458
	s_mul_i32 s18, s32, 0x1e0000
	s_lshl_b32 s19, s41, 8
	s_add_u32 s18, s18, s19
	s_add_i32 s19, s15, 1
	s_mul_i32 s22, s19, 0x7800000
	s_add_u32 s98, s18, s22
	s_lshl_b32 s26, s41, 18
	s_lshl_b32 s27, s32, 6
	s_add_u32 s26, s26, s27
	s_mul_i32 s27, s19, 0x3e00000
	s_add_u32 s26, s26, s27
	s_add_u32 s26, s26, 0x200000
	s_mov_b32 s22, 0xf000
	s_mov_b32 s28, 12
